# six conversion slots: a slot in the layer-1 input-projection partial round, layer-1 work spread so no slot exceeds its partial round
# baseline (speedup 1.0000x reference)
; #define LAS __attribute__((address_space(3)))
; __device__ __forceinline__ void prologue(const kptr_t kp, LAS float* scr, int gw, int NGW, int lane) {
;     unsigned char* ws = KPTR(unsigned char, 23);
;     for (int it = gw; it < IT_TOTAL; it += NGW) {
;         int r = it;
.Lrt_hop3:
	s_cmp_eq_u32 s101, 15
	s_cbranch_scc1 .Lslot_5_ret
	s_branch .Lrt_hop4

; #define LAS __attribute__((address_space(3)))
; __device__ __forceinline__ void prologue(const kptr_t kp, LAS float* scr, int gw, int NGW, int lane) {
;     unsigned char* ws = KPTR(unsigned char, 23);
;     for (int it = gw; it < IT_TOTAL; it += NGW) {
;         int r = it;
.LBB0_1054:
	s_cmp_lt_u32 s2, 16
	s_cbranch_scc1 .Lslot_3_skip
	v_writelane_b32 v250, s3, 0
	v_writelane_b32 v250, s4, 1
	v_writelane_b32 v250, s5, 2
	v_writelane_b32 v250, s6, 3
	v_writelane_b32 v250, s7, 4
	v_writelane_b32 v250, s8, 5
	v_writelane_b32 v250, s9, 6
	v_writelane_b32 v250, s10, 7
	v_writelane_b32 v250, s11, 8
	v_writelane_b32 v250, s12, 9
	v_writelane_b32 v250, s13, 10
	v_writelane_b32 v250, s14, 11
	v_writelane_b32 v250, s15, 12
	v_writelane_b32 v250, s16, 13
	v_writelane_b32 v250, s17, 14
	v_writelane_b32 v250, s18, 15
	v_writelane_b32 v250, s19, 16
	v_writelane_b32 v250, s20, 17
	v_writelane_b32 v250, s21, 18
	v_writelane_b32 v250, s22, 19
	v_writelane_b32 v250, s23, 20
	v_writelane_b32 v250, s24, 21
	v_writelane_b32 v250, s25, 22
	v_writelane_b32 v250, s26, 23
	v_writelane_b32 v250, s27, 24
	v_writelane_b32 v250, s28, 25
	v_writelane_b32 v250, s29, 26
	v_writelane_b32 v250, s30, 27
	v_writelane_b32 v250, s31, 28
	v_writelane_b32 v250, s32, 29
	v_writelane_b32 v250, s33, 30
	v_writelane_b32 v250, s34, 31
	v_writelane_b32 v250, s35, 32
	v_writelane_b32 v250, s36, 33
	v_writelane_b32 v250, s37, 34
	v_writelane_b32 v250, s38, 35
	v_writelane_b32 v250, s39, 36
	v_writelane_b32 v250, s40, 37
	v_writelane_b32 v250, s41, 38
	v_writelane_b32 v250, s42, 39
	v_writelane_b32 v250, s43, 40
	v_writelane_b32 v250, s44, 41
	v_writelane_b32 v250, s45, 42
	v_writelane_b32 v250, s46, 43
	v_writelane_b32 v250, s47, 44
	v_writelane_b32 v250, s48, 45
	v_writelane_b32 v250, s49, 46
	v_writelane_b32 v250, s50, 47
	v_writelane_b32 v250, s51, 48
	v_writelane_b32 v250, s52, 49
	v_writelane_b32 v250, s53, 50
	v_writelane_b32 v250, s54, 51
	v_writelane_b32 v250, s55, 52
	v_writelane_b32 v250, s56, 53
	v_writelane_b32 v250, s57, 54
	v_writelane_b32 v250, s58, 55
	v_writelane_b32 v250, s59, 56
	v_writelane_b32 v250, s60, 57
	v_writelane_b32 v250, s61, 58
	v_writelane_b32 v250, s62, 59
	v_writelane_b32 v250, s63, 60
	v_writelane_b32 v250, s64, 61
	v_writelane_b32 v250, s65, 62
	v_writelane_b32 v250, s66, 63
	v_writelane_b32 v251, s67, 0
	v_writelane_b32 v251, s68, 1
	v_writelane_b32 v251, s69, 2
	v_writelane_b32 v251, s70, 3
	v_writelane_b32 v251, s71, 4
	v_writelane_b32 v251, s72, 5
	v_writelane_b32 v251, s73, 6
	v_writelane_b32 v251, s74, 7
	v_writelane_b32 v251, s75, 8
	v_writelane_b32 v251, s76, 9
	v_writelane_b32 v251, s77, 10
	v_writelane_b32 v251, s78, 11
	v_writelane_b32 v251, s79, 12
	v_writelane_b32 v251, s80, 13
	v_writelane_b32 v251, s81, 14
	v_writelane_b32 v251, s82, 15
	v_writelane_b32 v251, s83, 16
	v_writelane_b32 v251, s84, 17
	v_writelane_b32 v251, s85, 18
	v_writelane_b32 v251, s86, 19
	v_writelane_b32 v251, s87, 20
	v_writelane_b32 v251, s88, 21
	v_writelane_b32 v251, s89, 22
	v_writelane_b32 v251, s90, 23
	v_writelane_b32 v251, s91, 24
	v_writelane_b32 v251, s92, 25
	v_writelane_b32 v251, s93, 26
	v_writelane_b32 v251, s94, 27
	v_writelane_b32 v251, s95, 28
	v_writelane_b32 v251, s96, 29
	v_writelane_b32 v251, s97, 30
	v_mov_b32_e32 v236, v200
	v_mov_b32_e32 v237, v201
	v_mov_b32_e32 v238, v202
	v_mov_b32_e32 v239, v203
	v_mov_b32_e32 v240, v204
	v_mov_b32_e32 v241, v205
	v_mov_b32_e32 v242, v206
	v_mov_b32_e32 v243, v207
	v_mov_b32_e32 v244, v208
	v_mov_b32_e32 v245, v209
	v_mov_b32_e32 v246, v210
	v_mov_b32_e32 v247, v211
	s_mov_b32 s98, 0x3a80
	s_mov_b32 s99, 0x780
	s_mov_b32 s100, 0x4600
	s_mov_b32 s101, 13
	s_branch .Lcv_hop2
.Lslot_3_ret:
	v_mov_b32_e32 v200, v236
	v_mov_b32_e32 v201, v237
	v_mov_b32_e32 v202, v238
	v_mov_b32_e32 v203, v239
	v_mov_b32_e32 v204, v240
	v_mov_b32_e32 v205, v241
	v_mov_b32_e32 v206, v242
	v_mov_b32_e32 v207, v243
	v_mov_b32_e32 v208, v244
	v_mov_b32_e32 v209, v245
	v_mov_b32_e32 v210, v246
	v_mov_b32_e32 v211, v247
	v_readlane_b32 s3, v250, 0
	v_readlane_b32 s4, v250, 1
	v_readlane_b32 s5, v250, 2
	v_readlane_b32 s6, v250, 3
	v_readlane_b32 s7, v250, 4
	v_readlane_b32 s8, v250, 5
	v_readlane_b32 s9, v250, 6
	v_readlane_b32 s10, v250, 7
	v_readlane_b32 s11, v250, 8
	v_readlane_b32 s12, v250, 9
	v_readlane_b32 s13, v250, 10
	v_readlane_b32 s14, v250, 11
	v_readlane_b32 s15, v250, 12
	v_readlane_b32 s16, v250, 13
	v_readlane_b32 s17, v250, 14
	v_readlane_b32 s18, v250, 15
	v_readlane_b32 s19, v250, 16
	v_readlane_b32 s20, v250, 17
	v_readlane_b32 s21, v250, 18
	v_readlane_b32 s22, v250, 19
	v_readlane_b32 s23, v250, 20
	v_readlane_b32 s24, v250, 21
	v_readlane_b32 s25, v250, 22
	v_readlane_b32 s26, v250, 23
	v_readlane_b32 s27, v250, 24
	v_readlane_b32 s28, v250, 25
	v_readlane_b32 s29, v250, 26
	v_readlane_b32 s30, v250, 27
	v_readlane_b32 s31, v250, 28
	v_readlane_b32 s32, v250, 29
	v_readlane_b32 s33, v250, 30
	v_readlane_b32 s34, v250, 31
	v_readlane_b32 s35, v250, 32
	v_readlane_b32 s36, v250, 33
	v_readlane_b32 s37, v250, 34
	v_readlane_b32 s38, v250, 35
	v_readlane_b32 s39, v250, 36
	v_readlane_b32 s40, v250, 37
	v_readlane_b32 s41, v250, 38
	v_readlane_b32 s42, v250, 39
	v_readlane_b32 s43, v250, 40
	v_readlane_b32 s44, v250, 41
	v_readlane_b32 s45, v250, 42
	v_readlane_b32 s46, v250, 43
	v_readlane_b32 s47, v250, 44
	v_readlane_b32 s48, v250, 45
	v_readlane_b32 s49, v250, 46
	v_readlane_b32 s50, v250, 47
	v_readlane_b32 s51, v250, 48
	v_readlane_b32 s52, v250, 49
	v_readlane_b32 s53, v250, 50
	v_readlane_b32 s54, v250, 51
	v_readlane_b32 s55, v250, 52
	v_readlane_b32 s56, v250, 53
	v_readlane_b32 s57, v250, 54
	v_readlane_b32 s58, v250, 55
	v_readlane_b32 s59, v250, 56
	v_readlane_b32 s60, v250, 57
	v_readlane_b32 s61, v250, 58
	v_readlane_b32 s62, v250, 59
	v_readlane_b32 s63, v250, 60
	v_readlane_b32 s64, v250, 61
	v_readlane_b32 s65, v250, 62
	v_readlane_b32 s66, v250, 63
	v_readlane_b32 s67, v251, 0
	v_readlane_b32 s68, v251, 1
	v_readlane_b32 s69, v251, 2
	v_readlane_b32 s70, v251, 3
	v_readlane_b32 s71, v251, 4
	v_readlane_b32 s72, v251, 5
	v_readlane_b32 s73, v251, 6
	v_readlane_b32 s74, v251, 7
	v_readlane_b32 s75, v251, 8
	v_readlane_b32 s76, v251, 9
	v_readlane_b32 s77, v251, 10
	v_readlane_b32 s78, v251, 11
	v_readlane_b32 s79, v251, 12
	v_readlane_b32 s80, v251, 13
	v_readlane_b32 s81, v251, 14
	v_readlane_b32 s82, v251, 15
	v_readlane_b32 s83, v251, 16
	v_readlane_b32 s84, v251, 17
	v_readlane_b32 s85, v251, 18
	v_readlane_b32 s86, v251, 19
	v_readlane_b32 s87, v251, 20
	v_readlane_b32 s88, v251, 21
	v_readlane_b32 s89, v251, 22
	v_readlane_b32 s90, v251, 23
	v_readlane_b32 s91, v251, 24
	v_readlane_b32 s92, v251, 25
	v_readlane_b32 s93, v251, 26
	v_readlane_b32 s94, v251, 27
	v_readlane_b32 s95, v251, 28
	v_readlane_b32 s96, v251, 29
	v_readlane_b32 s97, v251, 30
	s_nop 3

; #define LAS __attribute__((address_space(3)))
; __device__ __forceinline__ void prologue(const kptr_t kp, LAS float* scr, int gw, int NGW, int lane) {
;     unsigned char* ws = KPTR(unsigned char, 23);
;     for (int it = gw; it < IT_TOTAL; it += NGW) {
;         int r = it;
.LBB0_1270:
	s_cmp_lt_u32 s2, 44
	s_cbranch_scc1 .Lslot_4_skip
	v_writelane_b32 v250, s3, 0
	v_writelane_b32 v250, s4, 1
	v_writelane_b32 v250, s5, 2
	v_writelane_b32 v250, s6, 3
	v_writelane_b32 v250, s7, 4
	v_writelane_b32 v250, s8, 5
	v_writelane_b32 v250, s9, 6
	v_writelane_b32 v250, s10, 7
	v_writelane_b32 v250, s11, 8
	v_writelane_b32 v250, s12, 9
	v_writelane_b32 v250, s13, 10
	v_writelane_b32 v250, s14, 11
	v_writelane_b32 v250, s15, 12
	v_writelane_b32 v250, s16, 13
	v_writelane_b32 v250, s17, 14
	v_writelane_b32 v250, s18, 15
	v_writelane_b32 v250, s19, 16
	v_writelane_b32 v250, s20, 17
	v_writelane_b32 v250, s21, 18
	v_writelane_b32 v250, s22, 19
	v_writelane_b32 v250, s23, 20
	v_writelane_b32 v250, s24, 21
	v_writelane_b32 v250, s25, 22
	v_writelane_b32 v250, s26, 23
	v_writelane_b32 v250, s27, 24
	v_writelane_b32 v250, s28, 25
	v_writelane_b32 v250, s29, 26
	v_writelane_b32 v250, s30, 27
	v_writelane_b32 v250, s31, 28
	v_writelane_b32 v250, s32, 29
	v_writelane_b32 v250, s33, 30
	v_writelane_b32 v250, s34, 31
	v_writelane_b32 v250, s35, 32
	v_writelane_b32 v250, s36, 33
	v_writelane_b32 v250, s37, 34
	v_writelane_b32 v250, s38, 35
	v_writelane_b32 v250, s39, 36
	v_writelane_b32 v250, s40, 37
	v_writelane_b32 v250, s41, 38
	v_writelane_b32 v250, s42, 39
	v_writelane_b32 v250, s43, 40
	v_writelane_b32 v250, s44, 41
	v_writelane_b32 v250, s45, 42
	v_writelane_b32 v250, s46, 43
	v_writelane_b32 v250, s47, 44
	v_writelane_b32 v250, s48, 45
	v_writelane_b32 v250, s49, 46
	v_writelane_b32 v250, s50, 47
	v_writelane_b32 v250, s51, 48
	v_writelane_b32 v250, s52, 49
	v_writelane_b32 v250, s53, 50
	v_writelane_b32 v250, s54, 51
	v_writelane_b32 v250, s55, 52
	v_writelane_b32 v250, s56, 53
	v_writelane_b32 v250, s57, 54
	v_writelane_b32 v250, s58, 55
	v_writelane_b32 v250, s59, 56
	v_writelane_b32 v250, s60, 57
	v_writelane_b32 v250, s61, 58
	v_writelane_b32 v250, s62, 59
	v_writelane_b32 v250, s63, 60
	v_writelane_b32 v250, s64, 61
	v_writelane_b32 v250, s65, 62
	v_writelane_b32 v250, s66, 63
	v_writelane_b32 v251, s67, 0
	v_writelane_b32 v251, s68, 1
	v_writelane_b32 v251, s69, 2
	v_writelane_b32 v251, s70, 3
	v_writelane_b32 v251, s71, 4
	v_writelane_b32 v251, s72, 5
	v_writelane_b32 v251, s73, 6
	v_writelane_b32 v251, s74, 7
	v_writelane_b32 v251, s75, 8
	v_writelane_b32 v251, s76, 9
	v_writelane_b32 v251, s77, 10
	v_writelane_b32 v251, s78, 11
	v_writelane_b32 v251, s79, 12
	v_writelane_b32 v251, s80, 13
	v_writelane_b32 v251, s81, 14
	v_writelane_b32 v251, s82, 15
	v_writelane_b32 v251, s83, 16
	v_writelane_b32 v251, s84, 17
	v_writelane_b32 v251, s85, 18
	v_writelane_b32 v251, s86, 19
	v_writelane_b32 v251, s87, 20
	v_writelane_b32 v251, s88, 21
	v_writelane_b32 v251, s89, 22
	v_writelane_b32 v251, s90, 23
	v_writelane_b32 v251, s91, 24
	v_writelane_b32 v251, s92, 25
	v_writelane_b32 v251, s93, 26
	v_writelane_b32 v251, s94, 27
	v_writelane_b32 v251, s95, 28
	v_writelane_b32 v251, s96, 29
	v_writelane_b32 v251, s97, 30
	v_mov_b32_e32 v236, v200
	v_mov_b32_e32 v237, v201
	v_mov_b32_e32 v238, v202
	v_mov_b32_e32 v239, v203
	v_mov_b32_e32 v240, v204
	v_mov_b32_e32 v241, v205
	v_mov_b32_e32 v242, v206
	v_mov_b32_e32 v243, v207
	v_mov_b32_e32 v244, v208
	v_mov_b32_e32 v245, v209
	v_mov_b32_e32 v246, v210
	v_mov_b32_e32 v247, v211
	s_mov_b32 s98, 0x44a0
	s_mov_b32 s99, 0x6a0
	s_mov_b32 s100, 0x4b80
	s_mov_b32 s101, 14
	s_branch .Lcv_hop2
.Lslot_4_ret:
	s_cmp_eq_u32 s100, 0x4b80
	s_cbranch_scc0 .Lslot_4_done
	s_mov_b32 s98, 0xe0
	s_mov_b32 s100, 0x480
	s_branch .Lcv_hop2

; #define PG8_WAIT_V(n) asm volatile("s_waitcnt vmcnt(" #n ")" ::: "memory")
; #define PG8_BAR __builtin_amdgcn_s_barrier()
;     ...
;     PG8_WAIT_V(0);
;     if constexpr (!ALIGN_EPI) { if (wr == 0) PG8_BAR; }
;     PG8_BAR;
.LBB0_1489:
	s_waitcnt vmcnt(0)
	s_barrier
.LBB0_1490:
	s_branch .Lhop4_skip

; #define LAS __attribute__((address_space(3)))
; __device__ __forceinline__ void prologue(const kptr_t kp, LAS float* scr, int gw, int NGW, int lane) {
;     unsigned char* ws = KPTR(unsigned char, 23);
;     for (int it = gw; it < IT_TOTAL; it += NGW) {
;         int r = it;
.Lhop4_skip:
	s_cmp_lt_u32 s2, 44
	s_cbranch_scc1 .Lslot_5_skip
	v_writelane_b32 v250, s3, 0
	v_writelane_b32 v250, s4, 1
	v_writelane_b32 v250, s5, 2
	v_writelane_b32 v250, s6, 3
	v_writelane_b32 v250, s7, 4
	v_writelane_b32 v250, s8, 5
	v_writelane_b32 v250, s9, 6
	v_writelane_b32 v250, s10, 7
	v_writelane_b32 v250, s11, 8
	v_writelane_b32 v250, s12, 9
	v_writelane_b32 v250, s13, 10
	v_writelane_b32 v250, s14, 11
	v_writelane_b32 v250, s15, 12
	v_writelane_b32 v250, s16, 13
	v_writelane_b32 v250, s17, 14
	v_writelane_b32 v250, s18, 15
	v_writelane_b32 v250, s19, 16
	v_writelane_b32 v250, s20, 17
	v_writelane_b32 v250, s21, 18
	v_writelane_b32 v250, s22, 19
	v_writelane_b32 v250, s23, 20
	v_writelane_b32 v250, s24, 21
	v_writelane_b32 v250, s25, 22
	v_writelane_b32 v250, s26, 23
	v_writelane_b32 v250, s27, 24
	v_writelane_b32 v250, s28, 25
	v_writelane_b32 v250, s29, 26
	v_writelane_b32 v250, s30, 27
	v_writelane_b32 v250, s31, 28
	v_writelane_b32 v250, s32, 29
	v_writelane_b32 v250, s33, 30
	v_writelane_b32 v250, s34, 31
	v_writelane_b32 v250, s35, 32
	v_writelane_b32 v250, s36, 33
	v_writelane_b32 v250, s37, 34
	v_writelane_b32 v250, s38, 35
	v_writelane_b32 v250, s39, 36
	v_writelane_b32 v250, s40, 37
	v_writelane_b32 v250, s41, 38
	v_writelane_b32 v250, s42, 39
	v_writelane_b32 v250, s43, 40
	v_writelane_b32 v250, s44, 41
	v_writelane_b32 v250, s45, 42
	v_writelane_b32 v250, s46, 43
	v_writelane_b32 v250, s47, 44
	v_writelane_b32 v250, s48, 45
	v_writelane_b32 v250, s49, 46
	v_writelane_b32 v250, s50, 47
	v_writelane_b32 v250, s51, 48
	v_writelane_b32 v250, s52, 49
	v_writelane_b32 v250, s53, 50
	v_writelane_b32 v250, s54, 51
	v_writelane_b32 v250, s55, 52
	v_writelane_b32 v250, s56, 53
	v_writelane_b32 v250, s57, 54
	v_writelane_b32 v250, s58, 55
	v_writelane_b32 v250, s59, 56
	v_writelane_b32 v250, s60, 57
	v_writelane_b32 v250, s61, 58
	v_writelane_b32 v250, s62, 59
	v_writelane_b32 v250, s63, 60
	v_writelane_b32 v250, s64, 61
	v_writelane_b32 v250, s65, 62
	v_writelane_b32 v250, s66, 63
	v_writelane_b32 v251, s67, 0
	v_writelane_b32 v251, s68, 1
	v_writelane_b32 v251, s69, 2
	v_writelane_b32 v251, s70, 3
	v_writelane_b32 v251, s71, 4
	v_writelane_b32 v251, s72, 5
	v_writelane_b32 v251, s73, 6
	v_writelane_b32 v251, s74, 7
	v_writelane_b32 v251, s75, 8
	v_writelane_b32 v251, s76, 9
	v_writelane_b32 v251, s77, 10
	v_writelane_b32 v251, s78, 11
	v_writelane_b32 v251, s79, 12
	v_writelane_b32 v251, s80, 13
	v_writelane_b32 v251, s81, 14
	v_writelane_b32 v251, s82, 15
	v_writelane_b32 v251, s83, 16
	v_writelane_b32 v251, s84, 17
	v_writelane_b32 v251, s85, 18
	v_writelane_b32 v251, s86, 19
	v_writelane_b32 v251, s87, 20
	v_writelane_b32 v251, s88, 21
	v_writelane_b32 v251, s89, 22
	v_writelane_b32 v251, s90, 23
	v_writelane_b32 v251, s91, 24
	v_writelane_b32 v251, s92, 25
	v_writelane_b32 v251, s93, 26
	v_writelane_b32 v251, s94, 27
	v_writelane_b32 v251, s95, 28
	v_writelane_b32 v251, s96, 29
	v_writelane_b32 v251, s97, 30
	v_mov_b32_e32 v236, v200
	v_mov_b32_e32 v237, v201
	v_mov_b32_e32 v238, v202
	v_mov_b32_e32 v239, v203
	v_mov_b32_e32 v240, v204
	v_mov_b32_e32 v241, v205
	v_mov_b32_e32 v242, v206
	v_mov_b32_e32 v243, v207
	v_mov_b32_e32 v244, v208
	v_mov_b32_e32 v245, v209
	v_mov_b32_e32 v246, v210
	v_mov_b32_e32 v247, v211
	s_mov_b32 s98, 0x4a20
	s_mov_b32 s99, 0x6a0
	s_mov_b32 s100, 0x5880
	s_mov_b32 s101, 15
	s_branch .Lcv_hop3

; #define LAS __attribute__((address_space(3)))
; __device__ __forceinline__ void prologue(const kptr_t kp, LAS float* scr, int gw, int NGW, int lane) {
;     unsigned char* ws = KPTR(unsigned char, 23);
;     for (int it = gw; it < IT_TOTAL; it += NGW) {
;         int r = it;
.LBB0_2098:
	s_cmp_lt_u32 s2, 8
	s_cbranch_scc1 .Lslot_6_skip
	v_writelane_b32 v250, s3, 0
	v_writelane_b32 v250, s4, 1
	v_writelane_b32 v250, s5, 2
	v_writelane_b32 v250, s6, 3
	v_writelane_b32 v250, s7, 4
	v_writelane_b32 v250, s8, 5
	v_writelane_b32 v250, s9, 6
	v_writelane_b32 v250, s10, 7
	v_writelane_b32 v250, s11, 8
	v_writelane_b32 v250, s12, 9
	v_writelane_b32 v250, s13, 10
	v_writelane_b32 v250, s14, 11
	v_writelane_b32 v250, s15, 12
	v_writelane_b32 v250, s16, 13
	v_writelane_b32 v250, s17, 14
	v_writelane_b32 v250, s18, 15
	v_writelane_b32 v250, s19, 16
	v_writelane_b32 v250, s20, 17
	v_writelane_b32 v250, s21, 18
	v_writelane_b32 v250, s22, 19
	v_writelane_b32 v250, s23, 20
	v_writelane_b32 v250, s24, 21
	v_writelane_b32 v250, s25, 22
	v_writelane_b32 v250, s26, 23
	v_writelane_b32 v250, s27, 24
	v_writelane_b32 v250, s28, 25
	v_writelane_b32 v250, s29, 26
	v_writelane_b32 v250, s30, 27
	v_writelane_b32 v250, s31, 28
	v_writelane_b32 v250, s32, 29
	v_writelane_b32 v250, s33, 30
	v_writelane_b32 v250, s34, 31
	v_writelane_b32 v250, s35, 32
	v_writelane_b32 v250, s36, 33
	v_writelane_b32 v250, s37, 34
	v_writelane_b32 v250, s38, 35
	v_writelane_b32 v250, s39, 36
	v_writelane_b32 v250, s40, 37
	v_writelane_b32 v250, s41, 38
	v_writelane_b32 v250, s42, 39
	v_writelane_b32 v250, s43, 40
	v_writelane_b32 v250, s44, 41
	v_writelane_b32 v250, s45, 42
	v_writelane_b32 v250, s46, 43
	v_writelane_b32 v250, s47, 44
	v_writelane_b32 v250, s48, 45
	v_writelane_b32 v250, s49, 46
	v_writelane_b32 v250, s50, 47
	v_writelane_b32 v250, s51, 48
	v_writelane_b32 v250, s52, 49
	v_writelane_b32 v250, s53, 50
	v_writelane_b32 v250, s54, 51
	v_writelane_b32 v250, s55, 52
	v_writelane_b32 v250, s56, 53
	v_writelane_b32 v250, s57, 54
	v_writelane_b32 v250, s58, 55
	v_writelane_b32 v250, s59, 56
	v_writelane_b32 v250, s60, 57
	v_writelane_b32 v250, s61, 58
	v_writelane_b32 v250, s62, 59
	v_writelane_b32 v250, s63, 60
	v_writelane_b32 v250, s64, 61
	v_writelane_b32 v250, s65, 62
	v_writelane_b32 v250, s66, 63
	v_writelane_b32 v251, s67, 0
	v_writelane_b32 v251, s68, 1
	v_writelane_b32 v251, s69, 2
	v_writelane_b32 v251, s70, 3
	v_writelane_b32 v251, s71, 4
	v_writelane_b32 v251, s72, 5
	v_writelane_b32 v251, s73, 6
	v_writelane_b32 v251, s74, 7
	v_writelane_b32 v251, s75, 8
	v_writelane_b32 v251, s76, 9
	v_writelane_b32 v251, s77, 10
	v_writelane_b32 v251, s78, 11
	v_writelane_b32 v251, s79, 12
	v_writelane_b32 v251, s80, 13
	v_writelane_b32 v251, s81, 14
	v_writelane_b32 v251, s82, 15
	v_writelane_b32 v251, s83, 16
	v_writelane_b32 v251, s84, 17
	v_writelane_b32 v251, s85, 18
	v_writelane_b32 v251, s86, 19
	v_writelane_b32 v251, s87, 20
	v_writelane_b32 v251, s88, 21
	v_writelane_b32 v251, s89, 22
	v_writelane_b32 v251, s90, 23
	v_writelane_b32 v251, s91, 24
	v_writelane_b32 v251, s92, 25
	v_writelane_b32 v251, s93, 26
	v_writelane_b32 v251, s94, 27
	v_writelane_b32 v251, s95, 28
	v_writelane_b32 v251, s96, 29
	v_writelane_b32 v251, s97, 30
	v_mov_b32_e32 v236, v200
	v_mov_b32_e32 v237, v201
	v_mov_b32_e32 v238, v202
	v_mov_b32_e32 v239, v203
	v_mov_b32_e32 v240, v204
	v_mov_b32_e32 v241, v205
	v_mov_b32_e32 v242, v206
	v_mov_b32_e32 v243, v207
	v_mov_b32_e32 v244, v208
	v_mov_b32_e32 v245, v209
	v_mov_b32_e32 v246, v210
	v_mov_b32_e32 v247, v211
	s_mov_b32 s98, 0x5840
	s_mov_b32 s99, 0x7c0
	s_mov_b32 s100, 0x7180
	s_mov_b32 s101, 16
	s_branch .Lcv_hop4
; __device__ __forceinline__ unsigned xb_ld(unsigned* p)              { return __hip_atomic_load(p, __ATOMIC_RELAXED, __HIP_MEMORY_SCOPE_AGENT); }
; __device__ __forceinline__ void xcd_barrier_complete(unsigned* bar, unsigned x, unsigned& nloc, unsigned& nx) {
;     const unsigned G = gridDim.x * gridDim.y * gridDim.z;
;     unsigned sum, cnt, mine, sp = 0u;
;     for (;;) {
;         sum = 0u; cnt = 0u; mine = 0u;
; #pragma unroll
;         for (unsigned j = 0; j < 16; ++j) { const unsigned c = xb_ld(&bar[XB_XCNT(j)]); sum += c; cnt += (c > 0u) ? 1u : 0u; mine = (j == x) ? c : mine; }
; __device__ __forceinline__ void xcd_barrier(const XcdBarrier& b) {
;     asm volatile("s_waitcnt vmcnt(0)" ::: "memory");
;     __syncthreads();
;     if (threadIdx.x == 0) {
;         unsigned* bar = b.bar;
;         __builtin_amdgcn_s_waitcnt(0);
;         unsigned nloc = b.st[0], nx = b.st[1];
;         if (nloc == 0u) { xcd_barrier_complete(bar, b.x, nloc, nx); b.st[0] = nloc; b.st[1] = nx; }
.Lslot_6_ret:
	v_mov_b32_e32 v200, v236
	v_mov_b32_e32 v201, v237
	v_mov_b32_e32 v202, v238
	v_mov_b32_e32 v203, v239
	v_mov_b32_e32 v204, v240
	v_mov_b32_e32 v205, v241
	v_mov_b32_e32 v206, v242
	v_mov_b32_e32 v207, v243
	v_mov_b32_e32 v208, v244
	v_mov_b32_e32 v209, v245
	v_mov_b32_e32 v210, v246
	v_mov_b32_e32 v211, v247
	v_readlane_b32 s3, v250, 0
	v_readlane_b32 s4, v250, 1
	v_readlane_b32 s5, v250, 2
	v_readlane_b32 s6, v250, 3
	v_readlane_b32 s7, v250, 4
	v_readlane_b32 s8, v250, 5
	v_readlane_b32 s9, v250, 6
	v_readlane_b32 s10, v250, 7
	v_readlane_b32 s11, v250, 8
	v_readlane_b32 s12, v250, 9
	v_readlane_b32 s13, v250, 10
	v_readlane_b32 s14, v250, 11
	v_readlane_b32 s15, v250, 12
	v_readlane_b32 s16, v250, 13
	v_readlane_b32 s17, v250, 14
	v_readlane_b32 s18, v250, 15
	v_readlane_b32 s19, v250, 16
	v_readlane_b32 s20, v250, 17
	v_readlane_b32 s21, v250, 18
	v_readlane_b32 s22, v250, 19
	v_readlane_b32 s23, v250, 20
	v_readlane_b32 s24, v250, 21
	v_readlane_b32 s25, v250, 22
	v_readlane_b32 s26, v250, 23
	v_readlane_b32 s27, v250, 24
	v_readlane_b32 s28, v250, 25
	v_readlane_b32 s29, v250, 26
	v_readlane_b32 s30, v250, 27
	v_readlane_b32 s31, v250, 28
	v_readlane_b32 s32, v250, 29
	v_readlane_b32 s33, v250, 30
	v_readlane_b32 s34, v250, 31
	v_readlane_b32 s35, v250, 32
	v_readlane_b32 s36, v250, 33
	v_readlane_b32 s37, v250, 34
	v_readlane_b32 s38, v250, 35
	v_readlane_b32 s39, v250, 36
	v_readlane_b32 s40, v250, 37
	v_readlane_b32 s41, v250, 38
	v_readlane_b32 s42, v250, 39
	v_readlane_b32 s43, v250, 40
	v_readlane_b32 s44, v250, 41
	v_readlane_b32 s45, v250, 42
	v_readlane_b32 s46, v250, 43
	v_readlane_b32 s47, v250, 44
	v_readlane_b32 s48, v250, 45
	v_readlane_b32 s49, v250, 46
	v_readlane_b32 s50, v250, 47
	v_readlane_b32 s51, v250, 48
	v_readlane_b32 s52, v250, 49
	v_readlane_b32 s53, v250, 50
	v_readlane_b32 s54, v250, 51
	v_readlane_b32 s55, v250, 52
	v_readlane_b32 s56, v250, 53
	v_readlane_b32 s57, v250, 54
	v_readlane_b32 s58, v250, 55
	v_readlane_b32 s59, v250, 56
	v_readlane_b32 s60, v250, 57
	v_readlane_b32 s61, v250, 58
	v_readlane_b32 s62, v250, 59
	v_readlane_b32 s63, v250, 60
	v_readlane_b32 s64, v250, 61
	v_readlane_b32 s65, v250, 62
	v_readlane_b32 s66, v250, 63
	v_readlane_b32 s67, v251, 0
	v_readlane_b32 s68, v251, 1
	v_readlane_b32 s69, v251, 2
	v_readlane_b32 s70, v251, 3
	v_readlane_b32 s71, v251, 4
	v_readlane_b32 s72, v251, 5
	v_readlane_b32 s73, v251, 6
	v_readlane_b32 s74, v251, 7
	v_readlane_b32 s75, v251, 8
	v_readlane_b32 s76, v251, 9
	v_readlane_b32 s77, v251, 10
	v_readlane_b32 s78, v251, 11
	v_readlane_b32 s79, v251, 12
	v_readlane_b32 s80, v251, 13
	v_readlane_b32 s81, v251, 14
	v_readlane_b32 s82, v251, 15
	v_readlane_b32 s83, v251, 16
	v_readlane_b32 s84, v251, 17
	v_readlane_b32 s85, v251, 18
	v_readlane_b32 s86, v251, 19
	v_readlane_b32 s87, v251, 20
	v_readlane_b32 s88, v251, 21
	v_readlane_b32 s89, v251, 22
	v_readlane_b32 s90, v251, 23
	v_readlane_b32 s91, v251, 24
	v_readlane_b32 s92, v251, 25
	v_readlane_b32 s93, v251, 26
	v_readlane_b32 s94, v251, 27
	v_readlane_b32 s95, v251, 28
	v_readlane_b32 s96, v251, 29
	v_readlane_b32 s97, v251, 30
	s_nop 3
.Lslot_6_skip:
	s_mov_b64 s[10:11], s[0:1]
	s_getreg_b32 s8, hwreg(HW_REG_XCC_ID, 0, 4)
	s_waitcnt vmcnt(0)
	s_waitcnt vmcnt(0) lgkmcnt(0)
	s_barrier
	s_and_saveexec_b64 s[6:7], s[24:25]
	s_cbranch_execz .LBB0_2150
	s_add_i32 s9, 0, 0x27fc0
	v_mov_b32_e32 v0, s9
	s_load_dwordx2 s[10:11], s[10:11], 0xb8
	s_waitcnt vmcnt(0) expcnt(0) lgkmcnt(0)
	ds_read_b32 v2, v0
	s_add_i32 s9, 0, 0x27fc4
	v_mov_b32_e32 v0, s9
	ds_read_b32 v0, v0
	s_and_b32 s8, s8, 15
	s_waitcnt lgkmcnt(1)
	v_cmp_ne_u32_e32 vcc, 0, v2
	s_cbranch_vccnz .LBB0_2114
	v_readlane_b32 s12, v252, 0
	v_readlane_b32 s13, v252, 1
	s_load_dword s12, s[12:13], 0x14
	s_mov_b32 s9, 1
	v_mov_b32_e32 v16, 0
	s_waitcnt lgkmcnt(0)
	s_lshr_b32 s14, s12, 16
	s_and_b32 s12, s12, 0xffff
	s_cmp_lg_u32 s12, 0
	s_cselect_b64 s[12:13], -1, 0
	s_cmp_lg_u64 s[12:13], 0
	s_addc_u32 s12, s31, 0
	s_cmp_lg_u32 s14, 0
	s_mul_i32 s29, s12, s30
	s_cselect_b64 s[12:13], -1, 0
	s_cmp_lg_u64 s[12:13], 0
	s_addc_u32 s12, s72, 0
	s_mul_i32 s29, s29, s12
	s_add_u32 s12, s10, 0xc8200
	s_addc_u32 s13, s11, 0
	s_add_u32 s14, s10, 0xc8400
	s_addc_u32 s15, s11, 0
	s_add_u32 s16, s10, 0xc8500
	s_addc_u32 s17, s11, 0
	s_add_u32 s18, s10, 0xc8600
	s_addc_u32 s19, s11, 0
	s_add_u32 s20, s10, 0xc8700
	s_addc_u32 s21, s11, 0
	s_add_u32 s22, s10, 0xc8800
	s_addc_u32 s23, s11, 0
	s_add_u32 s26, s10, 0xc8900
	s_addc_u32 s27, s11, 0
	s_add_u32 s36, s10, 0xc8a00
	s_addc_u32 s37, s11, 0
	s_add_u32 s38, s10, 0xc8b00
	s_addc_u32 s39, s11, 0
	s_add_u32 s40, s10, 0xc8c00
	s_addc_u32 s41, s11, 0
	s_add_u32 s42, s10, 0xc8d00
	s_addc_u32 s43, s11, 0
	s_add_u32 s44, s10, 0xc8e00
	s_addc_u32 s45, s11, 0
	s_add_u32 s46, s10, 0xc8f00
	s_addc_u32 s47, s11, 0
	s_add_u32 s48, s10, 0xc9000
	s_addc_u32 s49, s11, 0
	s_add_u32 s50, s10, 0xc9100
	s_addc_u32 s51, s11, 0
	s_add_u32 s52, s10, 0xc9200
	s_addc_u32 s53, s11, 0
	s_add_u32 s54, s10, 0xc9300
	s_addc_u32 s55, s11, 0
	s_branch .LBB0_2102
